# weight-conversion streaming loops: wait for the next unit's loads moved from the finish-block entry to just before its first store (entry waits vmcnt(8))
# speedup vs baseline: 1.0064x; 1.0064x over previous
.LBB0_132:
	s_barrier
	s_waitcnt vmcnt(8)
	ds_write2_b32 v74, v2, v3 offset1:1
	ds_write2_b32 v74, v4, v5 offset0:2 offset1:3
	s_nop 0
	ds_write2_b32 v74, v6, v7 offset0:4 offset1:5
	ds_write2_b32 v74, v8, v9 offset0:6 offset1:7
	v_add_u32_e32 v2, 0x4100, v74
	s_nop 0
	ds_write2_b32 v2, v10, v11 offset1:1
	v_add_u32_e32 v2, 0x4108, v74
	ds_write2_b32 v2, v12, v13 offset1:1
	v_add_u32_e32 v2, 0x4110, v74
	s_nop 0
	ds_write2_b32 v2, v14, v15 offset1:1
	v_add_u32_e32 v2, 0x4118, v74
	ds_write2_b32 v2, v16, v17 offset1:1
	v_add_u32_e32 v2, 0x8200, v74
	s_nop 0
	ds_write2_b32 v2, v18, v19 offset1:1
	v_add_u32_e32 v2, 0x8208, v74
	ds_write2_b32 v2, v20, v21 offset1:1
	v_add_u32_e32 v2, 0x8210, v74
	s_nop 0
	ds_write2_b32 v2, v22, v23 offset1:1
	v_add_u32_e32 v2, 0x8218, v74
	ds_write2_b32 v2, v24, v25 offset1:1
	v_add_u32_e32 v2, 0xc300, v74
	s_nop 0
	ds_write2_b32 v2, v26, v27 offset1:1
	v_add_u32_e32 v2, 0xc308, v74
	ds_write2_b32 v2, v28, v29 offset1:1
	v_add_u32_e32 v2, 0xc310, v74
	s_nop 0
	ds_write2_b32 v2, v30, v31 offset1:1
	v_add_u32_e32 v2, 0xc318, v74
	ds_write2_b32 v2, v32, v33 offset1:1
	s_waitcnt lgkmcnt(0)
	s_barrier
	ds_read2_b32 v[2:3], v75 offset1:65
	ds_read2_b32 v[4:5], v75 offset0:130 offset1:195
	v_add_u32_e32 v8, 0x400, v75
	ds_read2_b32 v[6:7], v8 offset0:4 offset1:69
	ds_read2_b32 v[8:9], v8 offset0:134 offset1:199
	v_add_u32_e32 v10, 0x4400, v75
	s_waitcnt lgkmcnt(3)
	v_cvt_pk_bf16_f32 v2, v2, v3
	s_waitcnt lgkmcnt(2)
	v_cvt_pk_bf16_f32 v3, v4, v5
	s_waitcnt lgkmcnt(1)
	v_cvt_pk_bf16_f32 v4, v6, v7
	v_add_u32_e32 v6, 0x4000, v75
	v_add_u32_e32 v12, 0x4600, v75
	s_waitcnt lgkmcnt(0)
	v_cvt_pk_bf16_f32 v5, v8, v9
	ds_read2_b32 v[6:7], v6 offset0:64 offset1:129
	v_add_u32_e32 v8, 0x4200, v75
	ds_read2_b32 v[10:11], v10 offset0:68 offset1:133
	ds_read2_b32 v[12:13], v12 offset0:70 offset1:135
	ds_read2_b32 v[8:9], v8 offset0:66 offset1:131
	s_waitcnt vmcnt(0)
	global_store_dwordx4 v[70:71], v[2:5], off
	s_andn2_b64 vcc, exec, s[14:15]
	v_mov_b32_e32 v14, v42
	s_waitcnt lgkmcnt(3)
	v_cvt_pk_bf16_f32 v2, v6, v7
	s_waitcnt lgkmcnt(2)
	v_cvt_pk_bf16_f32 v4, v10, v11
	s_waitcnt lgkmcnt(1)
	v_cvt_pk_bf16_f32 v5, v12, v13
	v_add_u32_e32 v6, 0x8000, v75
	v_add_u32_e32 v10, 0x8400, v75
	v_add_u32_e32 v12, 0x8800, v75
	s_waitcnt lgkmcnt(0)
	v_cvt_pk_bf16_f32 v3, v8, v9
	ds_read2_b32 v[6:7], v6 offset0:128 offset1:193
	ds_read2_b32 v[8:9], v10 offset0:2 offset1:67
	ds_read2_b32 v[10:11], v10 offset0:132 offset1:197
	ds_read2_b32 v[12:13], v12 offset0:6 offset1:71
	global_store_dwordx4 v[70:71], v[2:5], off offset:128
	v_mov_b32_e32 v15, v43
	v_mov_b32_e32 v16, v44
	s_waitcnt lgkmcnt(3)
	v_cvt_pk_bf16_f32 v2, v6, v7
	s_waitcnt lgkmcnt(2)
	v_cvt_pk_bf16_f32 v3, v8, v9
	s_waitcnt lgkmcnt(1)
	v_cvt_pk_bf16_f32 v4, v10, v11
	s_waitcnt lgkmcnt(0)
	v_cvt_pk_bf16_f32 v5, v12, v13
	v_add_u32_e32 v6, 0xc200, v75
	v_add_u32_e32 v8, 0xc400, v75
	v_add_u32_e32 v10, 0xc600, v75
	v_add_u32_e32 v12, 0xc800, v75
	ds_read2_b32 v[6:7], v6 offset0:64 offset1:129
	ds_read2_b32 v[8:9], v8 offset0:66 offset1:131
	ds_read2_b32 v[10:11], v10 offset0:68 offset1:133
	ds_read2_b32 v[12:13], v12 offset0:70 offset1:135
	global_store_dwordx4 v[70:71], v[2:5], off offset:256
	v_mov_b32_e32 v17, v45
	v_mov_b32_e32 v18, v54
	s_waitcnt lgkmcnt(3)
	v_cvt_pk_bf16_f32 v2, v6, v7
	s_waitcnt lgkmcnt(2)
	v_cvt_pk_bf16_f32 v3, v8, v9
	s_waitcnt lgkmcnt(1)
	v_cvt_pk_bf16_f32 v4, v10, v11
	s_waitcnt lgkmcnt(0)
	v_cvt_pk_bf16_f32 v5, v12, v13
	global_store_dwordx4 v[70:71], v[2:5], off offset:384
	v_mov_b64_e32 v[70:71], v[72:73]
	v_mov_b32_e32 v6, v34
	v_mov_b32_e32 v2, v38
	v_mov_b32_e32 v3, v39
	v_mov_b32_e32 v4, v40
	v_mov_b32_e32 v5, v41
	v_mov_b32_e32 v7, v35
	v_mov_b32_e32 v8, v36
	v_mov_b32_e32 v9, v37
	v_mov_b32_e32 v10, v46
	v_mov_b32_e32 v11, v47
	v_mov_b32_e32 v12, v48
	v_mov_b32_e32 v13, v49
	v_mov_b32_e32 v19, v55
	v_mov_b32_e32 v20, v56
	v_mov_b32_e32 v21, v57
	v_mov_b32_e32 v22, v50
	v_mov_b32_e32 v23, v51
	v_mov_b32_e32 v24, v52
	v_mov_b32_e32 v25, v53
	v_mov_b32_e32 v26, v62
	v_mov_b32_e32 v27, v63
	v_mov_b32_e32 v28, v64
	v_mov_b32_e32 v29, v65
	v_mov_b32_e32 v30, v58
	v_mov_b32_e32 v31, v59
	v_mov_b32_e32 v32, v60
	v_mov_b32_e32 v33, v61
	s_cbranch_vccz .LBB0_147

.LBB0_288:
	s_barrier
	s_waitcnt vmcnt(8)
	ds_write2_b32 v69, v2, v3 offset1:1
	ds_write2_b32 v69, v4, v5 offset0:2 offset1:3
	s_nop 0
	ds_write2_b32 v69, v6, v7 offset0:4 offset1:5
	ds_write2_b32 v69, v8, v9 offset0:6 offset1:7
	v_add_u32_e32 v2, 0x4100, v69
	s_nop 0
	ds_write2_b32 v2, v10, v11 offset1:1
	v_add_u32_e32 v2, 0x4108, v69
	ds_write2_b32 v2, v12, v13 offset1:1
	v_add_u32_e32 v2, 0x4110, v69
	s_nop 0
	ds_write2_b32 v2, v14, v15 offset1:1
	v_add_u32_e32 v2, 0x4118, v69
	ds_write2_b32 v2, v16, v17 offset1:1
	v_add_u32_e32 v2, 0x8200, v69
	s_nop 0
	ds_write2_b32 v2, v18, v19 offset1:1
	v_add_u32_e32 v2, 0x8208, v69
	ds_write2_b32 v2, v20, v21 offset1:1
	v_add_u32_e32 v2, 0x8210, v69
	s_nop 0
	ds_write2_b32 v2, v22, v23 offset1:1
	v_add_u32_e32 v2, 0x8218, v69
	ds_write2_b32 v2, v24, v25 offset1:1
	v_add_u32_e32 v2, 0xc300, v69
	s_nop 0
	ds_write2_b32 v2, v26, v27 offset1:1
	v_add_u32_e32 v2, 0xc308, v69
	ds_write2_b32 v2, v28, v29 offset1:1
	v_add_u32_e32 v2, 0xc310, v69
	s_nop 0
	ds_write2_b32 v2, v30, v31 offset1:1
	v_add_u32_e32 v2, 0xc318, v69
	ds_write2_b32 v2, v32, v33 offset1:1
	s_waitcnt lgkmcnt(0)
	s_barrier
	ds_read2_b32 v[2:3], v76 offset1:65
	ds_read2_b32 v[4:5], v76 offset0:130 offset1:195
	v_add_u32_e32 v8, 0x400, v76
	ds_read2_b32 v[6:7], v8 offset0:4 offset1:69
	ds_read2_b32 v[8:9], v8 offset0:134 offset1:199
	v_add_u32_e32 v10, 0x4400, v76
	s_waitcnt lgkmcnt(3)
	v_cvt_pk_bf16_f32 v2, v2, v3
	s_waitcnt lgkmcnt(2)
	v_cvt_pk_bf16_f32 v3, v4, v5
	s_waitcnt lgkmcnt(1)
	v_cvt_pk_bf16_f32 v4, v6, v7
	v_add_u32_e32 v6, 0x4000, v76
	v_add_u32_e32 v12, 0x4600, v76
	s_waitcnt lgkmcnt(0)
	v_cvt_pk_bf16_f32 v5, v8, v9
	ds_read2_b32 v[6:7], v6 offset0:64 offset1:129
	v_add_u32_e32 v8, 0x4200, v76
	ds_read2_b32 v[10:11], v10 offset0:68 offset1:133
	ds_read2_b32 v[12:13], v12 offset0:70 offset1:135
	ds_read2_b32 v[8:9], v8 offset0:66 offset1:131
	s_waitcnt vmcnt(0)
	global_store_dwordx4 v[72:73], v[2:5], off
	s_add_i32 s64, s64, 1
	s_cmp_ge_u32 s72, s33
	s_waitcnt lgkmcnt(3)
	v_cvt_pk_bf16_f32 v2, v6, v7
	s_waitcnt lgkmcnt(2)
	v_cvt_pk_bf16_f32 v4, v10, v11
	s_waitcnt lgkmcnt(1)
	v_cvt_pk_bf16_f32 v5, v12, v13
	v_add_u32_e32 v6, 0x8000, v76
	v_add_u32_e32 v10, 0x8400, v76
	v_add_u32_e32 v12, 0x8800, v76
	s_waitcnt lgkmcnt(0)
	v_cvt_pk_bf16_f32 v3, v8, v9
	ds_read2_b32 v[6:7], v6 offset0:128 offset1:193
	ds_read2_b32 v[8:9], v10 offset0:2 offset1:67
	ds_read2_b32 v[10:11], v10 offset0:132 offset1:197
	ds_read2_b32 v[12:13], v12 offset0:6 offset1:71
	global_store_dwordx4 v[72:73], v[2:5], off offset:128
	v_mov_b32_e32 v14, v46
	v_mov_b32_e32 v15, v47
	s_waitcnt lgkmcnt(3)
	v_cvt_pk_bf16_f32 v2, v6, v7
	s_waitcnt lgkmcnt(2)
	v_cvt_pk_bf16_f32 v3, v8, v9
	s_waitcnt lgkmcnt(1)
	v_cvt_pk_bf16_f32 v4, v10, v11
	s_waitcnt lgkmcnt(0)
	v_cvt_pk_bf16_f32 v5, v12, v13
	v_add_u32_e32 v6, 0xc200, v76
	v_add_u32_e32 v8, 0xc400, v76
	v_add_u32_e32 v10, 0xc600, v76
	v_add_u32_e32 v12, 0xc800, v76
	ds_read2_b32 v[6:7], v6 offset0:64 offset1:129
	ds_read2_b32 v[8:9], v8 offset0:66 offset1:131
	ds_read2_b32 v[10:11], v10 offset0:68 offset1:133
	ds_read2_b32 v[12:13], v12 offset0:70 offset1:135
	global_store_dwordx4 v[72:73], v[2:5], off offset:256
	v_mov_b32_e32 v16, v48
	v_mov_b32_e32 v17, v49
	s_waitcnt lgkmcnt(3)
	v_cvt_pk_bf16_f32 v2, v6, v7
	s_waitcnt lgkmcnt(2)
	v_cvt_pk_bf16_f32 v3, v8, v9
	s_waitcnt lgkmcnt(1)
	v_cvt_pk_bf16_f32 v4, v10, v11
	s_waitcnt lgkmcnt(0)
	v_cvt_pk_bf16_f32 v5, v12, v13
	global_store_dwordx4 v[72:73], v[2:5], off offset:384
	v_mov_b64_e32 v[72:73], v[74:75]
	v_mov_b32_e32 v6, v34
	v_mov_b32_e32 v2, v38
	v_mov_b32_e32 v3, v39
	v_mov_b32_e32 v4, v40
	v_mov_b32_e32 v5, v41
	v_mov_b32_e32 v7, v35
	v_mov_b32_e32 v8, v36
	v_mov_b32_e32 v9, v37
	v_mov_b32_e32 v10, v42
	v_mov_b32_e32 v11, v43
	v_mov_b32_e32 v12, v44
	v_mov_b32_e32 v13, v45
	v_mov_b32_e32 v18, v50
	v_mov_b32_e32 v19, v51
	v_mov_b32_e32 v20, v52
	v_mov_b32_e32 v21, v53
	v_mov_b32_e32 v22, v54
	v_mov_b32_e32 v23, v55
	v_mov_b32_e32 v24, v56
	v_mov_b32_e32 v25, v57
	v_mov_b32_e32 v26, v58
	v_mov_b32_e32 v27, v59
	v_mov_b32_e32 v28, v60
	v_mov_b32_e32 v29, v61
	v_mov_b32_e32 v30, v62
	v_mov_b32_e32 v31, v63
	v_mov_b32_e32 v32, v64
	v_mov_b32_e32 v33, v65
	s_cbranch_scc1 .LBB0_294

.LBB0_705:
	s_barrier
	s_waitcnt vmcnt(8)
	ds_write2_b32 v74, v2, v3 offset1:1
	ds_write2_b32 v74, v4, v5 offset0:2 offset1:3
	s_nop 0
	ds_write2_b32 v74, v6, v7 offset0:4 offset1:5
	ds_write2_b32 v74, v8, v9 offset0:6 offset1:7
	v_add_u32_e32 v2, 0x4100, v74
	s_nop 0
	ds_write2_b32 v2, v10, v11 offset1:1
	v_add_u32_e32 v2, 0x4108, v74
	ds_write2_b32 v2, v12, v13 offset1:1
	v_add_u32_e32 v2, 0x4110, v74
	s_nop 0
	ds_write2_b32 v2, v14, v15 offset1:1
	v_add_u32_e32 v2, 0x4118, v74
	ds_write2_b32 v2, v16, v17 offset1:1
	v_add_u32_e32 v2, 0x8200, v74
	s_nop 0
	ds_write2_b32 v2, v18, v19 offset1:1
	v_add_u32_e32 v2, 0x8208, v74
	ds_write2_b32 v2, v20, v21 offset1:1
	v_add_u32_e32 v2, 0x8210, v74
	s_nop 0
	ds_write2_b32 v2, v22, v23 offset1:1
	v_add_u32_e32 v2, 0x8218, v74
	ds_write2_b32 v2, v24, v25 offset1:1
	v_add_u32_e32 v2, 0xc300, v74
	s_nop 0
	ds_write2_b32 v2, v26, v27 offset1:1
	v_add_u32_e32 v2, 0xc308, v74
	ds_write2_b32 v2, v28, v29 offset1:1
	v_add_u32_e32 v2, 0xc310, v74
	s_nop 0
	ds_write2_b32 v2, v30, v31 offset1:1
	v_add_u32_e32 v2, 0xc318, v74
	ds_write2_b32 v2, v32, v33 offset1:1
	s_waitcnt lgkmcnt(0)
	s_barrier
	ds_read2_b32 v[2:3], v75 offset1:65
	ds_read2_b32 v[4:5], v75 offset0:130 offset1:195
	v_add_u32_e32 v8, 0x400, v75
	ds_read2_b32 v[6:7], v8 offset0:4 offset1:69
	ds_read2_b32 v[8:9], v8 offset0:134 offset1:199
	v_add_u32_e32 v10, 0x4400, v75
	s_waitcnt lgkmcnt(3)
	v_cvt_pk_bf16_f32 v2, v2, v3
	s_waitcnt lgkmcnt(2)
	v_cvt_pk_bf16_f32 v3, v4, v5
	s_waitcnt lgkmcnt(1)
	v_cvt_pk_bf16_f32 v4, v6, v7
	v_add_u32_e32 v6, 0x4000, v75
	v_add_u32_e32 v12, 0x4600, v75
	s_waitcnt lgkmcnt(0)
	v_cvt_pk_bf16_f32 v5, v8, v9
	ds_read2_b32 v[6:7], v6 offset0:64 offset1:129
	v_add_u32_e32 v8, 0x4200, v75
	ds_read2_b32 v[10:11], v10 offset0:68 offset1:133
	ds_read2_b32 v[12:13], v12 offset0:70 offset1:135
	ds_read2_b32 v[8:9], v8 offset0:66 offset1:131
	s_waitcnt vmcnt(0)
	global_store_dwordx4 v[70:71], v[2:5], off
	s_cmpk_lt_i32 s25, 0x13d0
	s_mov_b32 s12, s25
	s_waitcnt lgkmcnt(3)
	v_cvt_pk_bf16_f32 v2, v6, v7
	s_waitcnt lgkmcnt(2)
	v_cvt_pk_bf16_f32 v4, v10, v11
	s_waitcnt lgkmcnt(1)
	v_cvt_pk_bf16_f32 v5, v12, v13
	v_add_u32_e32 v6, 0x8000, v75
	v_add_u32_e32 v10, 0x8400, v75
	v_add_u32_e32 v12, 0x8800, v75
	s_waitcnt lgkmcnt(0)
	v_cvt_pk_bf16_f32 v3, v8, v9
	ds_read2_b32 v[6:7], v6 offset0:128 offset1:193
	ds_read2_b32 v[8:9], v10 offset0:2 offset1:67
	ds_read2_b32 v[10:11], v10 offset0:132 offset1:197
	ds_read2_b32 v[12:13], v12 offset0:6 offset1:71
	global_store_dwordx4 v[70:71], v[2:5], off offset:128
	v_mov_b32_e32 v14, v42
	v_mov_b32_e32 v15, v43
	s_waitcnt lgkmcnt(3)
	v_cvt_pk_bf16_f32 v2, v6, v7
	s_waitcnt lgkmcnt(2)
	v_cvt_pk_bf16_f32 v3, v8, v9
	s_waitcnt lgkmcnt(1)
	v_cvt_pk_bf16_f32 v4, v10, v11
	s_waitcnt lgkmcnt(0)
	v_cvt_pk_bf16_f32 v5, v12, v13
	v_add_u32_e32 v6, 0xc200, v75
	v_add_u32_e32 v8, 0xc400, v75
	v_add_u32_e32 v10, 0xc600, v75
	v_add_u32_e32 v12, 0xc800, v75
	ds_read2_b32 v[6:7], v6 offset0:64 offset1:129
	ds_read2_b32 v[8:9], v8 offset0:66 offset1:131
	ds_read2_b32 v[10:11], v10 offset0:68 offset1:133
	ds_read2_b32 v[12:13], v12 offset0:70 offset1:135
	global_store_dwordx4 v[70:71], v[2:5], off offset:256
	v_mov_b32_e32 v16, v44
	v_mov_b32_e32 v17, v45
	s_waitcnt lgkmcnt(3)
	v_cvt_pk_bf16_f32 v2, v6, v7
	s_waitcnt lgkmcnt(2)
	v_cvt_pk_bf16_f32 v3, v8, v9
	s_waitcnt lgkmcnt(1)
	v_cvt_pk_bf16_f32 v4, v10, v11
	s_waitcnt lgkmcnt(0)
	v_cvt_pk_bf16_f32 v5, v12, v13
	global_store_dwordx4 v[70:71], v[2:5], off offset:384
	v_mov_b64_e32 v[70:71], v[72:73]
	v_mov_b32_e32 v6, v34
	v_mov_b32_e32 v2, v38
	v_mov_b32_e32 v3, v39
	v_mov_b32_e32 v4, v40
	v_mov_b32_e32 v5, v41
	v_mov_b32_e32 v7, v35
	v_mov_b32_e32 v8, v36
	v_mov_b32_e32 v9, v37
	v_mov_b32_e32 v10, v46
	v_mov_b32_e32 v11, v47
	v_mov_b32_e32 v12, v48
	v_mov_b32_e32 v13, v49
	v_mov_b32_e32 v18, v54
	v_mov_b32_e32 v19, v55
	v_mov_b32_e32 v20, v56
	v_mov_b32_e32 v21, v57
	v_mov_b32_e32 v22, v50
	v_mov_b32_e32 v23, v51
	v_mov_b32_e32 v24, v52
	v_mov_b32_e32 v25, v53
	v_mov_b32_e32 v26, v62
	v_mov_b32_e32 v27, v63
	v_mov_b32_e32 v28, v64
	v_mov_b32_e32 v29, v65
	v_mov_b32_e32 v30, v58
	v_mov_b32_e32 v31, v59
	v_mov_b32_e32 v32, v60
	v_mov_b32_e32 v33, v61
	s_cbranch_scc0 .LBB0_728

.LBB0_1302:
	s_barrier
	s_waitcnt vmcnt(8)
	ds_write2_b32 v74, v2, v3 offset1:1
	ds_write2_b32 v74, v4, v5 offset0:2 offset1:3
	s_nop 0
	ds_write2_b32 v74, v6, v7 offset0:4 offset1:5
	ds_write2_b32 v74, v8, v9 offset0:6 offset1:7
	v_add_u32_e32 v2, 0x4100, v74
	s_nop 0
	ds_write2_b32 v2, v10, v11 offset1:1
	v_add_u32_e32 v2, 0x4108, v74
	ds_write2_b32 v2, v12, v13 offset1:1
	v_add_u32_e32 v2, 0x4110, v74
	s_nop 0
	ds_write2_b32 v2, v14, v15 offset1:1
	v_add_u32_e32 v2, 0x4118, v74
	ds_write2_b32 v2, v16, v17 offset1:1
	v_add_u32_e32 v2, 0x8200, v74
	s_nop 0
	ds_write2_b32 v2, v18, v19 offset1:1
	v_add_u32_e32 v2, 0x8208, v74
	ds_write2_b32 v2, v20, v21 offset1:1
	v_add_u32_e32 v2, 0x8210, v74
	s_nop 0
	ds_write2_b32 v2, v22, v23 offset1:1
	v_add_u32_e32 v2, 0x8218, v74
	ds_write2_b32 v2, v24, v25 offset1:1
	v_add_u32_e32 v2, 0xc300, v74
	s_nop 0
	ds_write2_b32 v2, v26, v27 offset1:1
	v_add_u32_e32 v2, 0xc308, v74
	ds_write2_b32 v2, v28, v29 offset1:1
	v_add_u32_e32 v2, 0xc310, v74
	s_nop 0
	ds_write2_b32 v2, v30, v31 offset1:1
	v_add_u32_e32 v2, 0xc318, v74
	ds_write2_b32 v2, v32, v33 offset1:1
	s_waitcnt lgkmcnt(0)
	s_barrier
	ds_read2_b32 v[2:3], v75 offset1:65
	ds_read2_b32 v[4:5], v75 offset0:130 offset1:195
	v_add_u32_e32 v8, 0x400, v75
	ds_read2_b32 v[6:7], v8 offset0:4 offset1:69
	ds_read2_b32 v[8:9], v8 offset0:134 offset1:199
	v_add_u32_e32 v10, 0x4400, v75
	s_waitcnt lgkmcnt(3)
	v_cvt_pk_bf16_f32 v2, v2, v3
	s_waitcnt lgkmcnt(2)
	v_cvt_pk_bf16_f32 v3, v4, v5
	s_waitcnt lgkmcnt(1)
	v_cvt_pk_bf16_f32 v4, v6, v7
	v_add_u32_e32 v6, 0x4000, v75
	v_add_u32_e32 v12, 0x4600, v75
	s_waitcnt lgkmcnt(0)
	v_cvt_pk_bf16_f32 v5, v8, v9
	ds_read2_b32 v[6:7], v6 offset0:64 offset1:129
	v_add_u32_e32 v8, 0x4200, v75
	ds_read2_b32 v[10:11], v10 offset0:68 offset1:133
	ds_read2_b32 v[12:13], v12 offset0:70 offset1:135
	ds_read2_b32 v[8:9], v8 offset0:66 offset1:131
	s_waitcnt vmcnt(0)
	global_store_dwordx4 v[70:71], v[2:5], off
	s_cmpk_lt_i32 s23, 0x19d0
	s_mov_b32 s10, s23
	s_waitcnt lgkmcnt(3)
	v_cvt_pk_bf16_f32 v2, v6, v7
	s_waitcnt lgkmcnt(2)
	v_cvt_pk_bf16_f32 v4, v10, v11
	s_waitcnt lgkmcnt(1)
	v_cvt_pk_bf16_f32 v5, v12, v13
	v_add_u32_e32 v6, 0x8000, v75
	v_add_u32_e32 v10, 0x8400, v75
	v_add_u32_e32 v12, 0x8800, v75
	s_waitcnt lgkmcnt(0)
	v_cvt_pk_bf16_f32 v3, v8, v9
	ds_read2_b32 v[6:7], v6 offset0:128 offset1:193
	ds_read2_b32 v[8:9], v10 offset0:2 offset1:67
	ds_read2_b32 v[10:11], v10 offset0:132 offset1:197
	ds_read2_b32 v[12:13], v12 offset0:6 offset1:71
	global_store_dwordx4 v[70:71], v[2:5], off offset:128
	v_mov_b32_e32 v14, v42
	v_mov_b32_e32 v15, v43
	s_waitcnt lgkmcnt(3)
	v_cvt_pk_bf16_f32 v2, v6, v7
	s_waitcnt lgkmcnt(2)
	v_cvt_pk_bf16_f32 v3, v8, v9
	s_waitcnt lgkmcnt(1)
	v_cvt_pk_bf16_f32 v4, v10, v11
	s_waitcnt lgkmcnt(0)
	v_cvt_pk_bf16_f32 v5, v12, v13
	v_add_u32_e32 v6, 0xc200, v75
	v_add_u32_e32 v8, 0xc400, v75
	v_add_u32_e32 v10, 0xc600, v75
	v_add_u32_e32 v12, 0xc800, v75
	ds_read2_b32 v[6:7], v6 offset0:64 offset1:129
	ds_read2_b32 v[8:9], v8 offset0:66 offset1:131
	ds_read2_b32 v[10:11], v10 offset0:68 offset1:133
	ds_read2_b32 v[12:13], v12 offset0:70 offset1:135
	global_store_dwordx4 v[70:71], v[2:5], off offset:256
	v_mov_b32_e32 v16, v44
	v_mov_b32_e32 v17, v45
	s_waitcnt lgkmcnt(3)
	v_cvt_pk_bf16_f32 v2, v6, v7
	s_waitcnt lgkmcnt(2)
	v_cvt_pk_bf16_f32 v3, v8, v9
	s_waitcnt lgkmcnt(1)
	v_cvt_pk_bf16_f32 v4, v10, v11
	s_waitcnt lgkmcnt(0)
	v_cvt_pk_bf16_f32 v5, v12, v13
	global_store_dwordx4 v[70:71], v[2:5], off offset:384
	v_mov_b64_e32 v[70:71], v[72:73]
	v_mov_b32_e32 v6, v34
	v_mov_b32_e32 v2, v38
	v_mov_b32_e32 v3, v39
	v_mov_b32_e32 v4, v40
	v_mov_b32_e32 v5, v41
	v_mov_b32_e32 v7, v35
	v_mov_b32_e32 v8, v36
	v_mov_b32_e32 v9, v37
	v_mov_b32_e32 v10, v46
	v_mov_b32_e32 v11, v47
	v_mov_b32_e32 v12, v48
	v_mov_b32_e32 v13, v49
	v_mov_b32_e32 v18, v54
	v_mov_b32_e32 v19, v55
	v_mov_b32_e32 v20, v56
	v_mov_b32_e32 v21, v57
	v_mov_b32_e32 v22, v50
	v_mov_b32_e32 v23, v51
	v_mov_b32_e32 v24, v52
	v_mov_b32_e32 v25, v53
	v_mov_b32_e32 v26, v62
	v_mov_b32_e32 v27, v63
	v_mov_b32_e32 v28, v64
	v_mov_b32_e32 v29, v65
	v_mov_b32_e32 v30, v58
	v_mov_b32_e32 v31, v59
	v_mov_b32_e32 v32, v60
	v_mov_b32_e32 v33, v61
	s_cbranch_scc0 .LBB0_1325
